# Hyena filter loop (phase 4): all 16 h3 loads of a position issued up front with per-batch counted waits (was 4 batches each waited to zero)
# speedup vs baseline: 1.0554x; 1.0053x over previous
; template <int LO, int HI>
; DEV void run_phases(LAS unsigned char* lds, const int ph_lo, const int ph_hi, const int G, const int wave0, unsigned& nbar) {
;     ...
;                 for (int p = tid; p < L; p += NTHREADS) { const float* hp = h3 + (size_t)p * 64; float sf = 0.f, sb = 0.f;
; #pragma unroll
;                     for (int j4 = 0; j4 < 16; ++j4) { const f32x4 hv = *(const f32x4*)(hp + 4 * j4);
; #pragma unroll
;                         for (int e = 0; e < 4; ++e) { sf += hv[e] * w4[4 * j4 + e]; sb += hv[e] * w4[64 + 4 * j4 + e]; } }
.LBB0_776:
	global_load_dwordx4 v[2:5], v[138:139], off offset:-192
	global_load_dwordx4 v[6:9], v[138:139], off offset:-208
	global_load_dwordx4 v[10:13], v[138:139], off offset:-224
	global_load_dwordx4 v[14:17], v[138:139], off offset:-240
	global_load_dwordx4 v[192:195], v[138:139], off offset:-128
	global_load_dwordx4 v[38:41], v[138:139], off offset:-144
	global_load_dwordx4 v[42:45], v[138:139], off offset:-160
	global_load_dwordx4 v[46:49], v[138:139], off offset:-176
	global_load_dwordx4 v[196:199], v[138:139], off offset:-64
	global_load_dwordx4 v[70:73], v[138:139], off offset:-80
	global_load_dwordx4 v[74:77], v[138:139], off offset:-96
	global_load_dwordx4 v[78:81], v[138:139], off offset:-112
	global_load_dwordx4 v[200:203], v[138:139], off
	global_load_dwordx4 v[102:105], v[138:139], off offset:-16
	global_load_dwordx4 v[106:109], v[138:139], off offset:-32
	global_load_dwordx4 v[110:113], v[138:139], off offset:-48
	v_readlane_b32 s2, v251, 24
	v_cvt_f32_i32_e32 v161, v159
	s_nop 0
	v_mov_b32_e32 v18, s2
	ds_read_b128 v[22:25], v18
	v_readlane_b32 s2, v251, 27
	s_waitcnt vmcnt(12) lgkmcnt(0)
	v_fma_f32 v160, v14, v22, 0
	v_mov_b32_e32 v18, s2
	v_readlane_b32 s2, v251, 28
	ds_read_b128 v[18:21], v18
	v_fmac_f32_e32 v160, v15, v23
	v_mov_b32_e32 v22, s2
	ds_read_b128 v[26:29], v22
	v_fmac_f32_e32 v160, v16, v24
	v_readlane_b32 s2, v251, 29
	v_fmac_f32_e32 v160, v17, v25
	s_waitcnt lgkmcnt(0)
	v_fmac_f32_e32 v160, v10, v26
	v_mov_b32_e32 v22, s2
	v_readlane_b32 s2, v251, 30
	ds_read_b128 v[22:25], v22
	v_fmac_f32_e32 v160, v11, v27
	v_mov_b32_e32 v26, s2
	ds_read_b128 v[30:33], v26
	v_fmac_f32_e32 v160, v12, v28
	v_fmac_f32_e32 v160, v13, v29
	v_readlane_b32 s2, v251, 31
	s_waitcnt lgkmcnt(0)
	v_fmac_f32_e32 v160, v6, v30
	v_mov_b32_e32 v26, s2
	v_fmac_f32_e32 v160, v7, v31
	v_readlane_b32 s2, v251, 33
	v_fmac_f32_e32 v160, v8, v32
	ds_read_b128 v[26:29], v26
	v_mov_b32_e32 v30, s2
	v_fmac_f32_e32 v160, v9, v33
	ds_read_b128 v[30:33], v30
	v_readlane_b32 s2, v251, 34
	s_waitcnt lgkmcnt(0)
	v_fmac_f32_e32 v160, v2, v30
	v_fmac_f32_e32 v160, v3, v31
	v_mov_b32_e32 v30, s2
	v_fmac_f32_e32 v160, v4, v32
	ds_read_b128 v[34:37], v30
	v_fmac_f32_e32 v160, v5, v33
	v_readlane_b32 s2, v251, 35
	s_nop 1
	v_mov_b32_e32 v50, s2
	ds_read_b128 v[54:57], v50
	v_readlane_b32 s2, v251, 37
	s_waitcnt vmcnt(8) lgkmcnt(0)
	v_fmac_f32_e32 v160, v46, v54
	v_mov_b32_e32 v50, s2
	v_readlane_b32 s2, v251, 39
	ds_read_b128 v[50:53], v50
	v_fmac_f32_e32 v160, v47, v55
	v_mov_b32_e32 v54, s2
	ds_read_b128 v[58:61], v54
	v_fmac_f32_e32 v160, v48, v56
	v_readlane_b32 s2, v251, 41
	v_fmac_f32_e32 v160, v49, v57
	s_waitcnt lgkmcnt(0)
	v_fmac_f32_e32 v160, v42, v58
	v_mov_b32_e32 v54, s2
	v_readlane_b32 s2, v251, 42
	ds_read_b128 v[54:57], v54
	v_fmac_f32_e32 v160, v43, v59
	v_mov_b32_e32 v58, s2
	ds_read_b128 v[62:65], v58
	v_fmac_f32_e32 v160, v44, v60
	v_fmac_f32_e32 v160, v45, v61
	v_readlane_b32 s2, v251, 44
	s_waitcnt lgkmcnt(0)
	v_fmac_f32_e32 v160, v38, v62
	v_mov_b32_e32 v58, s2
	v_fmac_f32_e32 v160, v39, v63
	v_readlane_b32 s2, v251, 46
	v_fmac_f32_e32 v160, v40, v64
	ds_read_b128 v[58:61], v58
	v_mov_b32_e32 v62, s2
	v_fmac_f32_e32 v160, v41, v65
	ds_read_b128 v[62:65], v62
	v_readlane_b32 s2, v251, 48
	s_waitcnt lgkmcnt(0)
	v_fmac_f32_e32 v160, v192, v62
	v_fmac_f32_e32 v160, v193, v63
	v_mov_b32_e32 v62, s2
	v_fmac_f32_e32 v160, v194, v64
	ds_read_b128 v[66:69], v62
	v_fmac_f32_e32 v160, v195, v65
	v_readlane_b32 s2, v251, 50
	s_nop 1
	v_mov_b32_e32 v82, s2
	ds_read_b128 v[86:89], v82
	v_readlane_b32 s2, v251, 52
	s_waitcnt vmcnt(4) lgkmcnt(0)
	v_fmac_f32_e32 v160, v78, v86
	v_mov_b32_e32 v82, s2
	v_readlane_b32 s2, v251, 54
	ds_read_b128 v[82:85], v82
	v_fmac_f32_e32 v160, v79, v87
	v_mov_b32_e32 v86, s2
	ds_read_b128 v[90:93], v86
	v_fmac_f32_e32 v160, v80, v88
	v_readlane_b32 s2, v251, 56
	v_fmac_f32_e32 v160, v81, v89
	s_waitcnt lgkmcnt(0)
	v_fmac_f32_e32 v160, v74, v90
	v_mov_b32_e32 v86, s2
	v_readlane_b32 s2, v251, 58
	ds_read_b128 v[86:89], v86
	v_fmac_f32_e32 v160, v75, v91
	v_mov_b32_e32 v90, s2
	ds_read_b128 v[94:97], v90
	v_fmac_f32_e32 v160, v76, v92
	v_fmac_f32_e32 v160, v77, v93
	v_readlane_b32 s2, v251, 60
	s_waitcnt lgkmcnt(0)
	v_fmac_f32_e32 v160, v70, v94
	v_mov_b32_e32 v90, s2
	v_fmac_f32_e32 v160, v71, v95
	v_readlane_b32 s2, v251, 62
	v_fmac_f32_e32 v160, v72, v96
	ds_read_b128 v[90:93], v90
	v_mov_b32_e32 v94, s2
	v_fmac_f32_e32 v160, v73, v97
	ds_read_b128 v[94:97], v94
	v_readlane_b32 s2, v250, 0
	s_waitcnt lgkmcnt(0)
	v_fmac_f32_e32 v160, v196, v94
	v_fmac_f32_e32 v160, v197, v95
	v_mov_b32_e32 v94, s2
	v_fmac_f32_e32 v160, v198, v96
	ds_read_b128 v[98:101], v94
	v_fmac_f32_e32 v160, v199, v97
	v_readlane_b32 s2, v250, 2
	s_nop 1
	v_mov_b32_e32 v114, s2
	ds_read_b128 v[118:121], v114
	v_readlane_b32 s2, v250, 4
	s_waitcnt vmcnt(0) lgkmcnt(0)
; template <int LO, int HI>
; DEV void run_phases(LAS unsigned char* lds, const int ph_lo, const int ph_hi, const int G, const int wave0, unsigned& nbar) {
;     ...
;                 for (int p = tid; p < L; p += NTHREADS) { const float* hp = h3 + (size_t)p * 64; float sf = 0.f, sb = 0.f;
; #pragma unroll
;                     for (int j4 = 0; j4 < 16; ++j4) { const f32x4 hv = *(const f32x4*)(hp + 4 * j4);
; #pragma unroll
;                         for (int e = 0; e < 4; ++e) { sf += hv[e] * w4[4 * j4 + e]; sb += hv[e] * w4[64 + 4 * j4 + e]; } }
;                     const float t = (float)p / (float)(L - 1), dec = expf(-t * ad); sf *= dec; sb = (p == 0) ? 0.f : sb * dec;
;                     re[fftl::padi(p)] = sf; im[fftl::padi(p)] = 0.f; im[fftl::padi(p + L)] = 0.f;
;                     if (p > 0) re[fftl::padi(N - p)] = sb; else re[fftl::padi(L)] = 0.f;
;                     l1 += fabsf(sf) + fabsf(sb); }
	v_fmac_f32_e32 v160, v110, v118
	v_mov_b32_e32 v114, s2
	v_readlane_b32 s2, v250, 6
	ds_read_b128 v[114:117], v114
	v_fmac_f32_e32 v160, v111, v119
	v_mov_b32_e32 v118, s2
	ds_read_b128 v[122:125], v118
	v_fmac_f32_e32 v160, v112, v120
	v_readlane_b32 s2, v250, 8
	v_fmac_f32_e32 v160, v113, v121
	s_waitcnt lgkmcnt(0)
	v_fmac_f32_e32 v160, v106, v122
	v_mov_b32_e32 v118, s2
	v_readlane_b32 s2, v250, 10
	ds_read_b128 v[118:121], v118
	v_fmac_f32_e32 v160, v107, v123
	v_mov_b32_e32 v122, s2
	ds_read_b128 v[126:129], v122
	v_fmac_f32_e32 v160, v108, v124
	v_readlane_b32 s2, v250, 11
	v_fmac_f32_e32 v160, v109, v125
	s_waitcnt lgkmcnt(0)
	v_fmac_f32_e32 v160, v102, v126
	v_mov_b32_e32 v122, s2
	v_readlane_b32 s2, v250, 12
	ds_read_b128 v[122:125], v122
	v_fmac_f32_e32 v160, v103, v127
	v_mov_b32_e32 v126, s2
	ds_read_b128 v[162:165], v126
	v_fmac_f32_e32 v160, v104, v128
	v_fmac_f32_e32 v160, v105, v129
	v_readlane_b32 s2, v250, 13
	s_waitcnt lgkmcnt(0)
	v_fmac_f32_e32 v160, v200, v162
	v_mov_b32_e32 v126, s2
	v_div_scale_f32 v162, s[2:3], v151, v151, -v161
	v_fmac_f32_e32 v160, v201, v163
	v_rcp_f32_e32 v163, v162
	v_fmac_f32_e32 v160, v202, v164
	v_fmac_f32_e32 v160, v203, v165
	s_mov_b32 s2, 0x3fb8aa3b
	v_fma_f32 v164, -v162, v163, 1.0
	v_fmac_f32_e32 v163, v164, v163
	v_div_scale_f32 v164, vcc, -v161, v151, -v161
	v_mul_f32_e32 v165, v164, v163
	v_fma_f32 v166, -v162, v165, v164
	v_fmac_f32_e32 v165, v166, v163
	v_fma_f32 v162, -v162, v165, v164
	v_div_fmas_f32 v162, v162, v163, v165
	v_div_fixup_f32 v161, v162, v151, -v161
	v_mul_f32_e64 v161, |v137|, v161
	v_mul_f32_e32 v162, 0x3fb8aa3b, v161
	v_fma_f32 v163, v161, s2, -v162
	v_rndne_f32_e32 v164, v162
	v_fmac_f32_e32 v163, 0x32a5705f, v161
	v_sub_f32_e32 v162, v162, v164
	v_add_f32_e32 v162, v162, v163
	v_exp_f32_e32 v162, v162
	v_cvt_i32_f32_e32 v163, v164
	s_mov_b32 s2, 0xc2ce8ed0
	v_cmp_ngt_f32_e32 vcc, s2, v161
	s_mov_b32 s2, 0x42b17218
	v_ldexp_f32 v162, v162, v163
	v_cndmask_b32_e32 v162, 0, v162, vcc
	v_cmp_nlt_f32_e32 vcc, s2, v161
	ds_read_b128 v[126:129], v126
	s_nop 0
	v_cndmask_b32_e32 v161, v187, v162, vcc
	v_ashrrev_i32_e32 v162, 5, v159
	v_mul_f32_e32 v160, v161, v160
	v_lshl_add_u32 v162, v162, 4, v157
	ds_write2st64_b32 v162, v160, v1 offset1:144
	v_add_u32_e32 v162, s0, v159
	v_ashrrev_i32_e32 v162, 5, v162
	v_lshl_add_u32 v162, v162, 4, v155
	v_cmp_gt_i32_e32 vcc, 1, v159
	ds_write_b32 v162, v1
	s_and_saveexec_b64 s[2:3], vcc
	s_xor_b64 s[10:11], exec, s[2:3]
	v_mov_b32_e32 v162, s1
	ds_write_b32 v162, v1
	s_or_saveexec_b64 s[10:11], s[10:11]
	v_fma_f32 v14, v14, v18, 0
	v_fmac_f32_e32 v14, v15, v19
	v_fmac_f32_e32 v14, v16, v20
	v_fmac_f32_e32 v14, v17, v21
	v_fmac_f32_e32 v14, v10, v22
	v_fmac_f32_e32 v14, v11, v23
	v_fmac_f32_e32 v14, v12, v24
	v_fmac_f32_e32 v14, v13, v25
	v_fmac_f32_e32 v14, v6, v26
	v_fmac_f32_e32 v14, v7, v27
	v_fmac_f32_e32 v14, v8, v28
	v_fmac_f32_e32 v14, v9, v29
	v_fmac_f32_e32 v14, v2, v34
	v_fmac_f32_e32 v14, v3, v35
	v_fmac_f32_e32 v14, v4, v36
	v_fmac_f32_e32 v14, v5, v37
	v_fmac_f32_e32 v14, v46, v50
	v_fmac_f32_e32 v14, v47, v51
	v_fmac_f32_e32 v14, v48, v52
	v_fmac_f32_e32 v14, v49, v53
	v_fmac_f32_e32 v14, v42, v54
	v_fmac_f32_e32 v14, v43, v55
	v_fmac_f32_e32 v14, v44, v56
	v_fmac_f32_e32 v14, v45, v57
	v_fmac_f32_e32 v14, v38, v58
	v_fmac_f32_e32 v14, v39, v59
	v_fmac_f32_e32 v14, v40, v60
	v_fmac_f32_e32 v14, v41, v61
	v_fmac_f32_e32 v14, v192, v66
	v_fmac_f32_e32 v14, v193, v67
	v_fmac_f32_e32 v14, v194, v68
	v_fmac_f32_e32 v14, v195, v69
	v_fmac_f32_e32 v14, v78, v82
	v_fmac_f32_e32 v14, v79, v83
	v_fmac_f32_e32 v14, v80, v84
	v_fmac_f32_e32 v14, v81, v85
	v_fmac_f32_e32 v14, v74, v86
	v_fmac_f32_e32 v14, v75, v87
	v_fmac_f32_e32 v14, v76, v88
	v_fmac_f32_e32 v14, v77, v89
	v_fmac_f32_e32 v14, v70, v90
	v_fmac_f32_e32 v14, v71, v91
	v_fmac_f32_e32 v14, v72, v92
	v_fmac_f32_e32 v14, v73, v93
	v_fmac_f32_e32 v14, v196, v98
	v_fmac_f32_e32 v14, v197, v99
	v_fmac_f32_e32 v14, v198, v100
	v_fmac_f32_e32 v14, v199, v101
	v_fmac_f32_e32 v14, v110, v114
	v_fmac_f32_e32 v14, v111, v115
	v_fmac_f32_e32 v14, v112, v116
	v_fmac_f32_e32 v14, v113, v117
	v_fmac_f32_e32 v14, v106, v118
	v_fmac_f32_e32 v14, v107, v119
	v_fmac_f32_e32 v14, v108, v120
	v_fmac_f32_e32 v14, v109, v121
	v_fmac_f32_e32 v14, v102, v122
	v_fmac_f32_e32 v14, v103, v123
	v_fmac_f32_e32 v14, v104, v124
	v_fmac_f32_e32 v14, v105, v125
	s_waitcnt lgkmcnt(2)
	v_fmac_f32_e32 v14, v200, v126
	v_fmac_f32_e32 v14, v201, v127
	v_fmac_f32_e32 v14, v202, v128
	v_fmac_f32_e32 v14, v203, v129
	v_mul_f32_e32 v2, v161, v14
	s_xor_b64 exec, exec, s[10:11]
	s_cbranch_execz .LBB0_775
	v_ashrrev_i32_e32 v3, 5, v153
	v_lshl_add_u32 v3, v3, 4, v152
	ds_write_b32 v3, v2
	s_branch .LBB0_775
